# adds: nt cache policy on the once-read OG / Z / OATT stream loads of the post phase (P4)
# baseline (speedup 1.0000x reference)
; __device__ __forceinline__ unsigned pk2(float lo, float hi) { const f32x2 v = {lo, hi}; const hwbf16x2 r = __builtin_convertvector(v, hwbf16x2); return __builtin_bit_cast(unsigned, r); }
; __device__ __forceinline__ float bf_lo(unsigned v) { return __uint_as_float(v << 16); }
; __device__ __forceinline__ float bf_hi(unsigned v) { return __uint_as_float(v & 0xffff0000u); }
; __device__ __forceinline__ float silu_f(float x) { return x * __builtin_amdgcn_rcpf(1.0f + __expf(-x)); }
; __global__ void __launch_bounds__(NTHR) fwd(Args args) {
;     ...
;         for (int job = gw; job < M * NH; job += NGW) {
;             const int m = job >> 4, h = job & 15; const size_t o = (size_t)m * 2048 + h * 128 + 2 * lane;
;             const unsigned a = *(const unsigned*)((const bf16*)OG + o), c = *(const unsigned*)((const bf16*)OG + (size_t)M * 2048 + o);
;             const float o0 = bf_lo(a) + bf_lo(c), o1 = bf_hi(a) + bf_hi(c);
;             const float r = rsqrtf(wave_sum(o0 * o0 + o1 * o1) * (1.f / HD) + EPS);
;             const f32x2 nw = *(const f32x2*)(args.gdn_out_norm + 2 * lane); const unsigned zz = *(const unsigned*)(Z + o);
;             *(unsigned*)(MIX + (size_t)m * 4096 + h * 128 + 2 * lane) = pk2(o0 * r * nw.x * silu_f(bf_lo(zz)), o1 * r * nw.y * silu_f(bf_hi(zz)));
;             const float l0 = LSE[(size_t)m * 16 + h], l1 = LSE[((size_t)M + m) * 16 + h], l2 = LSE[((size_t)2 * M + m) * 16 + h];
;             const float lm = fmaxf(l0, fmaxf(l1, l2)); const float e0 = __expf(l0 - lm), e1 = __expf(l1 - lm), e2 = __expf(l2 - lm); const float ei = 1.0f / (e0 + e1 + e2);
;             const unsigned p0 = *(const unsigned*)(OATT + o), p1 = *(const unsigned*)(OATT + (size_t)M * 2048 + o), p2 = *(const unsigned*)(OATT + (size_t)2 * M * 2048 + o);
;             *(unsigned*)(MIX + (size_t)m * 4096 + 2048 + h * 128 + 2 * lane) = pk2((e0 * bf_lo(p0) + e1 * bf_lo(p1) + e2 * bf_lo(p2)) * ei, (e0 * bf_hi(p0) + e1 * bf_hi(p1) + e2 * bf_hi(p2)) * ei);
;         }
.LBB0_582:
	s_ashr_i32 s14, s19, 4
	s_and_b32 s20, s19, 15
	s_ashr_i32 s15, s14, 31
	s_lshl_b32 s21, s20, 7
	s_lshl_b64 s[16:17], s[14:15], 11
	s_or_b32 s16, s16, s21
	v_mov_b32_e32 v15, s17
	v_or_b32_e32 v14, s16, v0
	v_lshlrev_b64 v[14:15], 1, v[14:15]
	v_lshl_add_u64 v[16:17], s[22:23], 0, v[14:15]
	v_lshl_add_u64 v[18:19], s[0:1], 0, v[14:15]
	v_lshl_add_u64 v[20:21], s[34:35], 0, v[14:15]
	global_load_dword v23, v[16:17], off nt
	global_load_dword v25, v[18:19], off nt
	global_load_dword v27, v[20:21], off nt
	s_nop 0
	global_load_dwordx2 v[16:17], v[4:5], off
	s_lshl_b64 s[16:17], s[14:15], 13
	s_add_u32 s16, s2, s16
	s_addc_u32 s17, s3, s17
	s_lshl_b32 s21, s20, 8
	s_add_u32 s16, s16, s21
	s_addc_u32 s17, s17, 0
	s_lshl_b64 s[14:15], s[14:15], 6
	s_add_u32 s14, s6, s14
	s_addc_u32 s15, s7, s15
	s_lshl_b32 s21, s20, 2
	s_add_u32 s20, s14, s21
	v_mov_b32_e32 v22, s21
	s_addc_u32 s21, s15, 0
	global_load_dword v28, v22, s[14:15]
	global_load_dword v29, v12, s[20:21]
	global_load_dword v30, v13, s[20:21]
	v_lshl_add_u64 v[18:19], s[4:5], 0, v[14:15]
	v_lshl_add_u64 v[20:21], s[10:11], 0, v[14:15]
	v_lshl_add_u64 v[14:15], s[12:13], 0, v[14:15]
	global_load_dword v40, v[18:19], off nt
	global_load_dword v41, v[20:21], off nt
	global_load_dword v42, v[14:15], off nt
	s_add_i32 s19, s19, s94
	s_cmp_lt_i32 s19, 0x20000
	s_waitcnt vmcnt(9)
	v_lshlrev_b32_e32 v22, 16, v23
	s_waitcnt vmcnt(8)
	v_lshlrev_b32_e32 v24, 16, v25
	v_and_b32_e32 v23, 0xffff0000, v23
	v_and_b32_e32 v25, 0xffff0000, v25
	v_pk_add_f32 v[22:23], v[22:23], v[24:25]
	s_waitcnt vmcnt(7)
	v_lshlrev_b32_e32 v26, 16, v27
	v_pk_mul_f32 v[24:25], v[22:23], v[22:23]
	v_and_b32_e32 v27, 0xffff0000, v27
	v_add_f32_e32 v33, v24, v25
	v_mul_f32_e32 v31, 0xbfb8aa3b, v26
	ds_bpermute_b32 v34, v1, v33
	v_mul_f32_e32 v32, 0xbfb8aa3b, v27
	v_exp_f32_e32 v31, v31
	v_exp_f32_e32 v32, v32
	v_add_f32_e32 v24, 1.0, v31
	s_waitcnt lgkmcnt(0)
	v_add_f32_e32 v31, v33, v34
	v_add_f32_e32 v25, 1.0, v32
	ds_bpermute_b32 v32, v6, v31
	v_rcp_f32_e32 v24, v24
	v_rcp_f32_e32 v25, v25
	s_nop 0
	v_pk_mul_f32 v[24:25], v[24:25], v[26:27]
	s_waitcnt lgkmcnt(0)
	v_add_f32_e32 v26, v31, v32
	ds_bpermute_b32 v27, v7, v26
	s_waitcnt lgkmcnt(0)
	v_add_f32_e32 v26, v26, v27
	ds_bpermute_b32 v27, v8, v26
	s_waitcnt lgkmcnt(0)
	v_add_f32_e32 v26, v26, v27
	ds_bpermute_b32 v27, v9, v26
	s_waitcnt lgkmcnt(0)
	v_add_f32_e32 v26, v26, v27
	ds_bpermute_b32 v27, v10, v26
	s_waitcnt lgkmcnt(0)
	v_add_f32_e32 v26, v26, v27
	v_fmamk_f32 v26, v26, 0x3c000000, v11
	v_mul_f32_e32 v27, 0x4b800000, v26
	v_cmp_gt_f32_e32 vcc, s18, v26
	s_nop 1
	v_cndmask_b32_e32 v26, v26, v27, vcc
	v_rsq_f32_e32 v26, v26
	s_nop 0
	v_mul_f32_e32 v27, 0x45800000, v26
	v_cndmask_b32_e32 v26, v26, v27, vcc
	v_pk_mul_f32 v[22:23], v[22:23], v[26:27] op_sel_hi:[1,0]
	s_waitcnt vmcnt(6)
	v_pk_mul_f32 v[16:17], v[16:17], v[22:23]
	s_nop 0
	v_pk_mul_f32 v[16:17], v[24:25], v[16:17]
	s_nop 0
	v_cvt_pk_bf16_f32 v16, v16, v17
	global_store_dword v2, v16, s[16:17]
	s_waitcnt vmcnt(4)
	v_max3_f32 v16, v28, v29, v30
	v_sub_f32_e32 v18, v28, v16
	v_sub_f32_e32 v20, v29, v16
	v_sub_f32_e32 v16, v30, v16
	v_mul_f32_e32 v18, 0x3fb8aa3b, v18
	v_mul_f32_e32 v20, 0x3fb8aa3b, v20
	v_mul_f32_e32 v22, 0x3fb8aa3b, v16
	v_exp_f32_e32 v16, v18
	v_exp_f32_e32 v18, v20
	v_exp_f32_e32 v20, v22
	v_lshl_add_u64 v[14:15], s[16:17], 0, v[2:3]
	v_add_f32_e32 v22, v16, v18
	v_add_f32_e32 v22, v20, v22
	v_div_scale_f32 v23, s[14:15], v22, v22, 1.0
	v_rcp_f32_e32 v25, v23
	v_div_scale_f32 v24, vcc, 1.0, v22, 1.0
	v_fma_f32 v26, -v23, v25, 1.0
	v_fmac_f32_e32 v25, v26, v25
	v_mul_f32_e32 v26, v24, v25
	v_fma_f32 v27, -v23, v26, v24
	v_fmac_f32_e32 v26, v27, v25
	v_fma_f32 v23, -v23, v26, v24
	v_div_fmas_f32 v23, v23, v25, v26
	v_div_fixup_f32 v22, v23, v22, 1.0
	v_add_co_u32_e32 v14, vcc, 0x1000, v14
	s_waitcnt vmcnt(3)
	v_lshlrev_b32_e32 v24, 16, v40
	s_waitcnt vmcnt(2)
	v_lshlrev_b32_e32 v26, 16, v41
	v_and_b32_e32 v27, 0xffff0000, v41
	v_and_b32_e32 v25, 0xffff0000, v40
	v_pk_mul_f32 v[18:19], v[18:19], v[26:27] op_sel_hi:[0,1]
	s_waitcnt vmcnt(1)
	v_lshlrev_b32_e32 v28, 16, v42
	v_and_b32_e32 v29, 0xffff0000, v42
	v_pk_fma_f32 v[16:17], v[16:17], v[24:25], v[18:19] op_sel_hi:[0,1,1]
	v_pk_fma_f32 v[16:17], v[20:21], v[28:29], v[16:17] op_sel_hi:[0,1,1]
	v_pk_mul_f32 v[16:17], v[16:17], v[22:23] op_sel_hi:[1,0]
	v_addc_co_u32_e32 v15, vcc, 0, v15, vcc
	v_cvt_pk_bf16_f32 v16, v16, v17
	global_store_dword v[14:15], v16, off
	s_cbranch_scc1 .LBB0_582
